# experiment: FFN gate/up epilogue stores marked sc1 (write-through) so the grid barrier's L2 write-back has less to flush
# speedup vs baseline: 1.0022x; 1.0020x over previous
; #define LAS __attribute__((address_space(3)))
; __device__ __forceinline__ unsigned pk2(float lo, float hi) { f32x2 v = {lo, hi}; bf16x2_t b = __builtin_convertvector(v, bf16x2_t); return __builtin_bit_cast(unsigned, b); }
; __device__ __forceinline__ float silu_f(float g) { return g * __builtin_amdgcn_rcpf(1.f + __builtin_amdgcn_exp2f(g * -1.4426950408889634f)); }
;     __device__ __forceinline__ void operator()(const f32x4 (&acc)[2][2][4][2], const Unit& u, int wr, int wc, int fr, int fq, LAS unsigned char* lds, int tid, State& st) const {
;         const int row0 = u.pm * BM + wr * 64 + fr, col0 = u.pn * 128 + wc * 32 + 8 * fq;
;         const LAS float* RT = rstd_panel(st, lds, u.pm, tid);
; #pragma unroll
;         for (int ai = 0; ai < 2; ++ai) {
;             float rs[4];
; #pragma unroll
;             for (int m = 0; m < 4; ++m) rs[m] = RT[wr * 64 + fr + ai * HALF + m * 16];
; #pragma unroll
;             for (int m = 0; m < 4; ++m) {
;                 const int row = row0 + ai * HALF + m * 16; const float r = rs[m];
;                 const f32x4 g0 = acc[ai][0][m][0] * r, g1 = acc[ai][0][m][1] * r, u0 = acc[ai][1][m][0] * r, u1 = acc[ai][1][m][1] * r;
;                 u32x4 w;
;                 w.x = pk2(silu_f(g0[0]) * u0[0], silu_f(g0[1]) * u0[1]); w.y = pk2(silu_f(g0[2]) * u0[2], silu_f(g0[3]) * u0[3]);
;                 w.z = pk2(silu_f(g1[0]) * u1[0], silu_f(g1[1]) * u1[1]); w.w = pk2(silu_f(g1[2]) * u1[2], silu_f(g1[3]) * u1[3]);
;                 *(u32x4*)(H + (size_t)row * DFF + col0) = w;
.LBB0_725:
	ds_read2_b32 v[154:155], v150 offset1:16
	ds_read2_b32 v[142:143], v150 offset0:32 offset1:48
	ds_read2_b32 v[156:157], v150 offset0:128 offset1:144
	ds_read2_b32 v[144:145], v150 offset0:160 offset1:176
	s_andn2_b64 vcc, exec, s[42:43]
	v_lshl_or_b32 v216, s21, 7, v151
	v_lshl_add_u32 v217, s9, 8, v147
	v_mov_b32_e32 v204, 1.0
	v_mul_u32_u24_e32 v214, 0x1600, v217
	v_lshl_add_u32 v214, v216, 1, v214
	s_waitcnt lgkmcnt(0)
	v_mul_f32_e32 v200, 0xbfb8aa3b, v154
	v_mul_f32_e32 v202, v154, v154
	v_mov_b32_e32 v215, v214
	v_pk_mul_f32 v[206:207], v[128:129], v[200:201] op_sel_hi:[1,0]
	v_pk_mul_f32 v[208:209], v[130:131], v[200:201] op_sel_hi:[1,0]
	v_pk_mul_f32 v[210:211], v[124:125], v[200:201] op_sel_hi:[1,0]
	v_pk_mul_f32 v[212:213], v[126:127], v[200:201] op_sel_hi:[1,0]
	v_exp_f32_e32 v206, v206
	v_exp_f32_e32 v207, v207
	v_exp_f32_e32 v208, v208
	v_exp_f32_e32 v209, v209
	v_exp_f32_e32 v210, v210
	v_exp_f32_e32 v211, v211
	v_exp_f32_e32 v212, v212
	v_exp_f32_e32 v213, v213
	v_pk_mul_f32 v[120:121], v[128:129], v[120:121]
	v_pk_mul_f32 v[122:123], v[130:131], v[122:123]
	v_pk_mul_f32 v[116:117], v[124:125], v[116:117]
	v_pk_mul_f32 v[118:119], v[126:127], v[118:119]
	v_pk_add_f32 v[206:207], v[206:207], v[204:205] op_sel_hi:[1,0]
	v_pk_add_f32 v[208:209], v[208:209], v[204:205] op_sel_hi:[1,0]
	v_pk_add_f32 v[210:211], v[210:211], v[204:205] op_sel_hi:[1,0]
	v_pk_add_f32 v[212:213], v[212:213], v[204:205] op_sel_hi:[1,0]
	v_rcp_f32_e32 v206, v206
	v_rcp_f32_e32 v207, v207
	v_rcp_f32_e32 v208, v208
	v_rcp_f32_e32 v209, v209
	v_rcp_f32_e32 v210, v210
	v_rcp_f32_e32 v211, v211
	v_rcp_f32_e32 v212, v212
	v_rcp_f32_e32 v213, v213
	v_pk_mul_f32 v[120:121], v[120:121], v[202:203] op_sel_hi:[1,0]
	v_pk_mul_f32 v[122:123], v[122:123], v[202:203] op_sel_hi:[1,0]
	v_pk_mul_f32 v[116:117], v[116:117], v[202:203] op_sel_hi:[1,0]
	v_pk_mul_f32 v[118:119], v[118:119], v[202:203] op_sel_hi:[1,0]
	v_pk_mul_f32 v[120:121], v[120:121], v[206:207]
	v_pk_mul_f32 v[122:123], v[122:123], v[208:209]
	v_pk_mul_f32 v[116:117], v[116:117], v[210:211]
	v_pk_mul_f32 v[118:119], v[118:119], v[212:213]
	v_cvt_pk_bf16_f32 v120, v120, v121
	v_cvt_pk_bf16_f32 v121, v122, v123
	v_cvt_pk_bf16_f32 v122, v116, v117
	v_cvt_pk_bf16_f32 v123, v118, v119
	global_store_dwordx4 v215, v[120:123], s[94:95] sc1
	v_mul_f32_e32 v200, 0xbfb8aa3b, v155
	v_mul_f32_e32 v202, v155, v155
	v_add_u32_e32 v215, 0x16000, v214
	v_pk_mul_f32 v[206:207], v[112:113], v[200:201] op_sel_hi:[1,0]
	v_pk_mul_f32 v[208:209], v[114:115], v[200:201] op_sel_hi:[1,0]
	v_pk_mul_f32 v[210:211], v[108:109], v[200:201] op_sel_hi:[1,0]
	v_pk_mul_f32 v[212:213], v[110:111], v[200:201] op_sel_hi:[1,0]
	v_exp_f32_e32 v206, v206
	v_exp_f32_e32 v207, v207
	v_exp_f32_e32 v208, v208
	v_exp_f32_e32 v209, v209
	v_exp_f32_e32 v210, v210
	v_exp_f32_e32 v211, v211
	v_exp_f32_e32 v212, v212
	v_exp_f32_e32 v213, v213
	v_pk_mul_f32 v[104:105], v[112:113], v[104:105]
	v_pk_mul_f32 v[106:107], v[114:115], v[106:107]
	v_pk_mul_f32 v[100:101], v[108:109], v[100:101]
	v_pk_mul_f32 v[102:103], v[110:111], v[102:103]
	v_pk_add_f32 v[206:207], v[206:207], v[204:205] op_sel_hi:[1,0]
	v_pk_add_f32 v[208:209], v[208:209], v[204:205] op_sel_hi:[1,0]
	v_pk_add_f32 v[210:211], v[210:211], v[204:205] op_sel_hi:[1,0]
	v_pk_add_f32 v[212:213], v[212:213], v[204:205] op_sel_hi:[1,0]
	v_rcp_f32_e32 v206, v206
	v_rcp_f32_e32 v207, v207
	v_rcp_f32_e32 v208, v208
	v_rcp_f32_e32 v209, v209
	v_rcp_f32_e32 v210, v210
	v_rcp_f32_e32 v211, v211
	v_rcp_f32_e32 v212, v212
	v_rcp_f32_e32 v213, v213
	v_pk_mul_f32 v[104:105], v[104:105], v[202:203] op_sel_hi:[1,0]
	v_pk_mul_f32 v[106:107], v[106:107], v[202:203] op_sel_hi:[1,0]
	v_pk_mul_f32 v[100:101], v[100:101], v[202:203] op_sel_hi:[1,0]
	v_pk_mul_f32 v[102:103], v[102:103], v[202:203] op_sel_hi:[1,0]
	v_pk_mul_f32 v[104:105], v[104:105], v[206:207]
	v_pk_mul_f32 v[106:107], v[106:107], v[208:209]
	v_pk_mul_f32 v[100:101], v[100:101], v[210:211]
	v_pk_mul_f32 v[102:103], v[102:103], v[212:213]
	v_cvt_pk_bf16_f32 v104, v104, v105
	v_cvt_pk_bf16_f32 v105, v106, v107
	v_cvt_pk_bf16_f32 v106, v100, v101
	v_cvt_pk_bf16_f32 v107, v102, v103
	global_store_dwordx4 v215, v[104:107], s[94:95] sc1
	v_mul_f32_e32 v200, 0xbfb8aa3b, v142
	v_mul_f32_e32 v202, v142, v142
	v_add_u32_e32 v215, 0x2c000, v214
	v_pk_mul_f32 v[206:207], v[96:97], v[200:201] op_sel_hi:[1,0]
	v_pk_mul_f32 v[208:209], v[98:99], v[200:201] op_sel_hi:[1,0]
	v_pk_mul_f32 v[210:211], v[92:93], v[200:201] op_sel_hi:[1,0]
	v_pk_mul_f32 v[212:213], v[94:95], v[200:201] op_sel_hi:[1,0]
	v_exp_f32_e32 v206, v206
	v_exp_f32_e32 v207, v207
	v_exp_f32_e32 v208, v208
	v_exp_f32_e32 v209, v209
	v_exp_f32_e32 v210, v210
	v_exp_f32_e32 v211, v211
	v_exp_f32_e32 v212, v212
	v_exp_f32_e32 v213, v213
	v_pk_mul_f32 v[88:89], v[96:97], v[88:89]
	v_pk_mul_f32 v[90:91], v[98:99], v[90:91]
	v_pk_mul_f32 v[84:85], v[92:93], v[84:85]
	v_pk_mul_f32 v[86:87], v[94:95], v[86:87]
	v_pk_add_f32 v[206:207], v[206:207], v[204:205] op_sel_hi:[1,0]
	v_pk_add_f32 v[208:209], v[208:209], v[204:205] op_sel_hi:[1,0]
	v_pk_add_f32 v[210:211], v[210:211], v[204:205] op_sel_hi:[1,0]
	v_pk_add_f32 v[212:213], v[212:213], v[204:205] op_sel_hi:[1,0]
	v_rcp_f32_e32 v206, v206
	v_rcp_f32_e32 v207, v207
	v_rcp_f32_e32 v208, v208
	v_rcp_f32_e32 v209, v209
	v_rcp_f32_e32 v210, v210
	v_rcp_f32_e32 v211, v211
	v_rcp_f32_e32 v212, v212
	v_rcp_f32_e32 v213, v213
	v_pk_mul_f32 v[88:89], v[88:89], v[202:203] op_sel_hi:[1,0]
	v_pk_mul_f32 v[90:91], v[90:91], v[202:203] op_sel_hi:[1,0]
	v_pk_mul_f32 v[84:85], v[84:85], v[202:203] op_sel_hi:[1,0]
	v_pk_mul_f32 v[86:87], v[86:87], v[202:203] op_sel_hi:[1,0]
; __device__ __forceinline__ unsigned pk2(float lo, float hi) { f32x2 v = {lo, hi}; bf16x2_t b = __builtin_convertvector(v, bf16x2_t); return __builtin_bit_cast(unsigned, b); }
; __device__ __forceinline__ float silu_f(float g) { return g * __builtin_amdgcn_rcpf(1.f + __builtin_amdgcn_exp2f(g * -1.4426950408889634f)); }
;     __device__ __forceinline__ void operator()(const f32x4 (&acc)[2][2][4][2], const Unit& u, int wr, int wc, int fr, int fq, LAS unsigned char* lds, int tid, State& st) const {
;     ...
;             for (int m = 0; m < 4; ++m) {
;                 const int row = row0 + ai * HALF + m * 16; const float r = rs[m];
;                 const f32x4 g0 = acc[ai][0][m][0] * r, g1 = acc[ai][0][m][1] * r, u0 = acc[ai][1][m][0] * r, u1 = acc[ai][1][m][1] * r;
;                 u32x4 w;
;                 w.x = pk2(silu_f(g0[0]) * u0[0], silu_f(g0[1]) * u0[1]); w.y = pk2(silu_f(g0[2]) * u0[2], silu_f(g0[3]) * u0[3]);
;                 w.z = pk2(silu_f(g1[0]) * u1[0], silu_f(g1[1]) * u1[1]); w.w = pk2(silu_f(g1[2]) * u1[2], silu_f(g1[3]) * u1[3]);
;                 *(u32x4*)(H + (size_t)row * DFF + col0) = w;
;             }
	v_pk_mul_f32 v[88:89], v[88:89], v[206:207]
	v_pk_mul_f32 v[90:91], v[90:91], v[208:209]
	v_pk_mul_f32 v[84:85], v[84:85], v[210:211]
	v_pk_mul_f32 v[86:87], v[86:87], v[212:213]
	v_cvt_pk_bf16_f32 v88, v88, v89
	v_cvt_pk_bf16_f32 v89, v90, v91
	v_cvt_pk_bf16_f32 v90, v84, v85
	v_cvt_pk_bf16_f32 v91, v86, v87
	global_store_dwordx4 v215, v[88:91], s[94:95] sc1
	v_mul_f32_e32 v200, 0xbfb8aa3b, v143
	v_mul_f32_e32 v202, v143, v143
	v_add_u32_e32 v215, 0x42000, v214
	v_pk_mul_f32 v[206:207], v[80:81], v[200:201] op_sel_hi:[1,0]
	v_pk_mul_f32 v[208:209], v[82:83], v[200:201] op_sel_hi:[1,0]
	v_pk_mul_f32 v[210:211], v[76:77], v[200:201] op_sel_hi:[1,0]
	v_pk_mul_f32 v[212:213], v[78:79], v[200:201] op_sel_hi:[1,0]
	v_exp_f32_e32 v206, v206
	v_exp_f32_e32 v207, v207
	v_exp_f32_e32 v208, v208
	v_exp_f32_e32 v209, v209
	v_exp_f32_e32 v210, v210
	v_exp_f32_e32 v211, v211
	v_exp_f32_e32 v212, v212
	v_exp_f32_e32 v213, v213
	v_pk_mul_f32 v[72:73], v[80:81], v[72:73]
	v_pk_mul_f32 v[74:75], v[82:83], v[74:75]
	v_pk_mul_f32 v[68:69], v[76:77], v[68:69]
	v_pk_mul_f32 v[70:71], v[78:79], v[70:71]
	v_pk_add_f32 v[206:207], v[206:207], v[204:205] op_sel_hi:[1,0]
	v_pk_add_f32 v[208:209], v[208:209], v[204:205] op_sel_hi:[1,0]
	v_pk_add_f32 v[210:211], v[210:211], v[204:205] op_sel_hi:[1,0]
	v_pk_add_f32 v[212:213], v[212:213], v[204:205] op_sel_hi:[1,0]
	v_rcp_f32_e32 v206, v206
	v_rcp_f32_e32 v207, v207
	v_rcp_f32_e32 v208, v208
	v_rcp_f32_e32 v209, v209
	v_rcp_f32_e32 v210, v210
	v_rcp_f32_e32 v211, v211
	v_rcp_f32_e32 v212, v212
	v_rcp_f32_e32 v213, v213
	v_pk_mul_f32 v[72:73], v[72:73], v[202:203] op_sel_hi:[1,0]
	v_pk_mul_f32 v[74:75], v[74:75], v[202:203] op_sel_hi:[1,0]
	v_pk_mul_f32 v[68:69], v[68:69], v[202:203] op_sel_hi:[1,0]
	v_pk_mul_f32 v[70:71], v[70:71], v[202:203] op_sel_hi:[1,0]
	v_pk_mul_f32 v[72:73], v[72:73], v[206:207]
	v_pk_mul_f32 v[74:75], v[74:75], v[208:209]
	v_pk_mul_f32 v[68:69], v[68:69], v[210:211]
	v_pk_mul_f32 v[70:71], v[70:71], v[212:213]
	v_cvt_pk_bf16_f32 v72, v72, v73
	v_cvt_pk_bf16_f32 v73, v74, v75
	v_cvt_pk_bf16_f32 v74, v68, v69
	v_cvt_pk_bf16_f32 v75, v70, v71
	global_store_dwordx4 v215, v[72:75], s[94:95] sc1
	v_mul_f32_e32 v200, 0xbfb8aa3b, v156
	v_mul_f32_e32 v202, v156, v156
	v_add_u32_e32 v215, 0xb0000, v214
	v_pk_mul_f32 v[206:207], v[64:65], v[200:201] op_sel_hi:[1,0]
	v_pk_mul_f32 v[208:209], v[66:67], v[200:201] op_sel_hi:[1,0]
	v_pk_mul_f32 v[210:211], v[60:61], v[200:201] op_sel_hi:[1,0]
	v_pk_mul_f32 v[212:213], v[62:63], v[200:201] op_sel_hi:[1,0]
	v_exp_f32_e32 v206, v206
	v_exp_f32_e32 v207, v207
	v_exp_f32_e32 v208, v208
	v_exp_f32_e32 v209, v209
	v_exp_f32_e32 v210, v210
	v_exp_f32_e32 v211, v211
	v_exp_f32_e32 v212, v212
	v_exp_f32_e32 v213, v213
	v_pk_mul_f32 v[56:57], v[64:65], v[56:57]
	v_pk_mul_f32 v[58:59], v[66:67], v[58:59]
	v_pk_mul_f32 v[52:53], v[60:61], v[52:53]
	v_pk_mul_f32 v[54:55], v[62:63], v[54:55]
	v_pk_add_f32 v[206:207], v[206:207], v[204:205] op_sel_hi:[1,0]
	v_pk_add_f32 v[208:209], v[208:209], v[204:205] op_sel_hi:[1,0]
	v_pk_add_f32 v[210:211], v[210:211], v[204:205] op_sel_hi:[1,0]
	v_pk_add_f32 v[212:213], v[212:213], v[204:205] op_sel_hi:[1,0]
	v_rcp_f32_e32 v206, v206
	v_rcp_f32_e32 v207, v207
	v_rcp_f32_e32 v208, v208
	v_rcp_f32_e32 v209, v209
	v_rcp_f32_e32 v210, v210
	v_rcp_f32_e32 v211, v211
	v_rcp_f32_e32 v212, v212
	v_rcp_f32_e32 v213, v213
	v_pk_mul_f32 v[56:57], v[56:57], v[202:203] op_sel_hi:[1,0]
	v_pk_mul_f32 v[58:59], v[58:59], v[202:203] op_sel_hi:[1,0]
	v_pk_mul_f32 v[52:53], v[52:53], v[202:203] op_sel_hi:[1,0]
	v_pk_mul_f32 v[54:55], v[54:55], v[202:203] op_sel_hi:[1,0]
	v_pk_mul_f32 v[56:57], v[56:57], v[206:207]
	v_pk_mul_f32 v[58:59], v[58:59], v[208:209]
	v_pk_mul_f32 v[52:53], v[52:53], v[210:211]
	v_pk_mul_f32 v[54:55], v[54:55], v[212:213]
	v_cvt_pk_bf16_f32 v56, v56, v57
	v_cvt_pk_bf16_f32 v57, v58, v59
	v_cvt_pk_bf16_f32 v58, v52, v53
	v_cvt_pk_bf16_f32 v59, v54, v55
	global_store_dwordx4 v215, v[56:59], s[94:95] sc1
	v_mul_f32_e32 v200, 0xbfb8aa3b, v157
	v_mul_f32_e32 v202, v157, v157
	v_add_u32_e32 v215, 0xc6000, v214
	v_pk_mul_f32 v[206:207], v[48:49], v[200:201] op_sel_hi:[1,0]
	v_pk_mul_f32 v[208:209], v[50:51], v[200:201] op_sel_hi:[1,0]
	v_pk_mul_f32 v[210:211], v[44:45], v[200:201] op_sel_hi:[1,0]
	v_pk_mul_f32 v[212:213], v[46:47], v[200:201] op_sel_hi:[1,0]
	v_exp_f32_e32 v206, v206
	v_exp_f32_e32 v207, v207
	v_exp_f32_e32 v208, v208
	v_exp_f32_e32 v209, v209
	v_exp_f32_e32 v210, v210
	v_exp_f32_e32 v211, v211
	v_exp_f32_e32 v212, v212
	v_exp_f32_e32 v213, v213
	v_pk_mul_f32 v[40:41], v[48:49], v[40:41]
	v_pk_mul_f32 v[42:43], v[50:51], v[42:43]
	v_pk_mul_f32 v[36:37], v[44:45], v[36:37]
	v_pk_mul_f32 v[38:39], v[46:47], v[38:39]
	v_pk_add_f32 v[206:207], v[206:207], v[204:205] op_sel_hi:[1,0]
	v_pk_add_f32 v[208:209], v[208:209], v[204:205] op_sel_hi:[1,0]
; __device__ __forceinline__ unsigned pk2(float lo, float hi) { f32x2 v = {lo, hi}; bf16x2_t b = __builtin_convertvector(v, bf16x2_t); return __builtin_bit_cast(unsigned, b); }
; __device__ __forceinline__ float silu_f(float g) { return g * __builtin_amdgcn_rcpf(1.f + __builtin_amdgcn_exp2f(g * -1.4426950408889634f)); }
; __device__ __forceinline__ void rstd_unit_start(RstdState& st, const float* ssq, int pm, int tid) {
;     if (pm != st.last_pm && tid < 256) st.pre = *(const f32x4*)(ssq + (size_t)(pm * BM + tid) * 4);
;     __device__ __forceinline__ void operator()(const f32x4 (&acc)[2][2][4][2], const Unit& u, int wr, int wc, int fr, int fq, LAS unsigned char* lds, int tid, State& st) const {
;     ...
;             for (int m = 0; m < 4; ++m) {
;                 const int row = row0 + ai * HALF + m * 16; const float r = rs[m];
;                 const f32x4 g0 = acc[ai][0][m][0] * r, g1 = acc[ai][0][m][1] * r, u0 = acc[ai][1][m][0] * r, u1 = acc[ai][1][m][1] * r;
;                 u32x4 w;
;                 w.x = pk2(silu_f(g0[0]) * u0[0], silu_f(g0[1]) * u0[1]); w.y = pk2(silu_f(g0[2]) * u0[2], silu_f(g0[3]) * u0[3]);
;                 w.z = pk2(silu_f(g1[0]) * u1[0], silu_f(g1[1]) * u1[1]); w.w = pk2(silu_f(g1[2]) * u1[2], silu_f(g1[3]) * u1[3]);
;                 *(u32x4*)(H + (size_t)row * DFF + col0) = w;
;             }
	v_pk_add_f32 v[210:211], v[210:211], v[204:205] op_sel_hi:[1,0]
	v_pk_add_f32 v[212:213], v[212:213], v[204:205] op_sel_hi:[1,0]
	v_rcp_f32_e32 v206, v206
	v_rcp_f32_e32 v207, v207
	v_rcp_f32_e32 v208, v208
	v_rcp_f32_e32 v209, v209
	v_rcp_f32_e32 v210, v210
	v_rcp_f32_e32 v211, v211
	v_rcp_f32_e32 v212, v212
	v_rcp_f32_e32 v213, v213
	v_pk_mul_f32 v[40:41], v[40:41], v[202:203] op_sel_hi:[1,0]
	v_pk_mul_f32 v[42:43], v[42:43], v[202:203] op_sel_hi:[1,0]
	v_pk_mul_f32 v[36:37], v[36:37], v[202:203] op_sel_hi:[1,0]
	v_pk_mul_f32 v[38:39], v[38:39], v[202:203] op_sel_hi:[1,0]
	v_pk_mul_f32 v[40:41], v[40:41], v[206:207]
	v_pk_mul_f32 v[42:43], v[42:43], v[208:209]
	v_pk_mul_f32 v[36:37], v[36:37], v[210:211]
	v_pk_mul_f32 v[38:39], v[38:39], v[212:213]
	v_cvt_pk_bf16_f32 v40, v40, v41
	v_cvt_pk_bf16_f32 v41, v42, v43
	v_cvt_pk_bf16_f32 v42, v36, v37
	v_cvt_pk_bf16_f32 v43, v38, v39
	global_store_dwordx4 v215, v[40:43], s[94:95] sc1
	v_mul_f32_e32 v200, 0xbfb8aa3b, v144
	v_mul_f32_e32 v202, v144, v144
	v_add_u32_e32 v215, 0xdc000, v214
	v_pk_mul_f32 v[206:207], v[32:33], v[200:201] op_sel_hi:[1,0]
	v_pk_mul_f32 v[208:209], v[34:35], v[200:201] op_sel_hi:[1,0]
	v_pk_mul_f32 v[210:211], v[28:29], v[200:201] op_sel_hi:[1,0]
	v_pk_mul_f32 v[212:213], v[30:31], v[200:201] op_sel_hi:[1,0]
	v_exp_f32_e32 v206, v206
	v_exp_f32_e32 v207, v207
	v_exp_f32_e32 v208, v208
	v_exp_f32_e32 v209, v209
	v_exp_f32_e32 v210, v210
	v_exp_f32_e32 v211, v211
	v_exp_f32_e32 v212, v212
	v_exp_f32_e32 v213, v213
	v_pk_mul_f32 v[24:25], v[32:33], v[24:25]
	v_pk_mul_f32 v[26:27], v[34:35], v[26:27]
	v_pk_mul_f32 v[20:21], v[28:29], v[20:21]
	v_pk_mul_f32 v[22:23], v[30:31], v[22:23]
	v_pk_add_f32 v[206:207], v[206:207], v[204:205] op_sel_hi:[1,0]
	v_pk_add_f32 v[208:209], v[208:209], v[204:205] op_sel_hi:[1,0]
	v_pk_add_f32 v[210:211], v[210:211], v[204:205] op_sel_hi:[1,0]
	v_pk_add_f32 v[212:213], v[212:213], v[204:205] op_sel_hi:[1,0]
	v_rcp_f32_e32 v206, v206
	v_rcp_f32_e32 v207, v207
	v_rcp_f32_e32 v208, v208
	v_rcp_f32_e32 v209, v209
	v_rcp_f32_e32 v210, v210
	v_rcp_f32_e32 v211, v211
	v_rcp_f32_e32 v212, v212
	v_rcp_f32_e32 v213, v213
	v_pk_mul_f32 v[24:25], v[24:25], v[202:203] op_sel_hi:[1,0]
	v_pk_mul_f32 v[26:27], v[26:27], v[202:203] op_sel_hi:[1,0]
	v_pk_mul_f32 v[20:21], v[20:21], v[202:203] op_sel_hi:[1,0]
	v_pk_mul_f32 v[22:23], v[22:23], v[202:203] op_sel_hi:[1,0]
	v_pk_mul_f32 v[24:25], v[24:25], v[206:207]
	v_pk_mul_f32 v[26:27], v[26:27], v[208:209]
	v_pk_mul_f32 v[20:21], v[20:21], v[210:211]
	v_pk_mul_f32 v[22:23], v[22:23], v[212:213]
	v_cvt_pk_bf16_f32 v24, v24, v25
	v_cvt_pk_bf16_f32 v25, v26, v27
	v_cvt_pk_bf16_f32 v26, v20, v21
	v_cvt_pk_bf16_f32 v27, v22, v23
	global_store_dwordx4 v215, v[24:27], s[94:95] sc1
	v_mul_f32_e32 v200, 0xbfb8aa3b, v145
	v_mul_f32_e32 v202, v145, v145
	v_add_u32_e32 v215, 0xf2000, v214
	v_pk_mul_f32 v[206:207], v[16:17], v[200:201] op_sel_hi:[1,0]
	v_pk_mul_f32 v[208:209], v[18:19], v[200:201] op_sel_hi:[1,0]
	v_pk_mul_f32 v[210:211], v[12:13], v[200:201] op_sel_hi:[1,0]
	v_pk_mul_f32 v[212:213], v[14:15], v[200:201] op_sel_hi:[1,0]
	v_exp_f32_e32 v206, v206
	v_exp_f32_e32 v207, v207
	v_exp_f32_e32 v208, v208
	v_exp_f32_e32 v209, v209
	v_exp_f32_e32 v210, v210
	v_exp_f32_e32 v211, v211
	v_exp_f32_e32 v212, v212
	v_exp_f32_e32 v213, v213
	v_pk_mul_f32 v[8:9], v[16:17], v[8:9]
	v_pk_mul_f32 v[10:11], v[18:19], v[10:11]
	v_pk_mul_f32 v[4:5], v[12:13], v[4:5]
	v_pk_mul_f32 v[6:7], v[14:15], v[6:7]
	v_pk_add_f32 v[206:207], v[206:207], v[204:205] op_sel_hi:[1,0]
	v_pk_add_f32 v[208:209], v[208:209], v[204:205] op_sel_hi:[1,0]
	v_pk_add_f32 v[210:211], v[210:211], v[204:205] op_sel_hi:[1,0]
	v_pk_add_f32 v[212:213], v[212:213], v[204:205] op_sel_hi:[1,0]
	v_rcp_f32_e32 v206, v206
	v_rcp_f32_e32 v207, v207
	v_rcp_f32_e32 v208, v208
	v_rcp_f32_e32 v209, v209
	v_rcp_f32_e32 v210, v210
	v_rcp_f32_e32 v211, v211
	v_rcp_f32_e32 v212, v212
	v_rcp_f32_e32 v213, v213
	v_pk_mul_f32 v[8:9], v[8:9], v[202:203] op_sel_hi:[1,0]
	v_pk_mul_f32 v[10:11], v[10:11], v[202:203] op_sel_hi:[1,0]
	v_pk_mul_f32 v[4:5], v[4:5], v[202:203] op_sel_hi:[1,0]
	v_pk_mul_f32 v[6:7], v[6:7], v[202:203] op_sel_hi:[1,0]
	v_pk_mul_f32 v[8:9], v[8:9], v[206:207]
	v_pk_mul_f32 v[10:11], v[10:11], v[208:209]
	v_pk_mul_f32 v[4:5], v[4:5], v[210:211]
	v_pk_mul_f32 v[6:7], v[6:7], v[212:213]
	v_cvt_pk_bf16_f32 v8, v8, v9
	v_cvt_pk_bf16_f32 v9, v10, v11
	v_cvt_pk_bf16_f32 v10, v4, v5
	v_cvt_pk_bf16_f32 v11, v6, v7
	global_store_dwordx4 v215, v[8:11], s[94:95] sc1
	s_mov_b64 s[6:7], -1
	s_cbranch_vccnz .LBB0_713
	s_cmp_lg_u32 s22, s9
	s_cselect_b64 s[6:7], -1, 0
	s_and_b64 s[14:15], s[38:39], s[6:7]
	s_and_saveexec_b64 s[6:7], s[14:15]
	s_cbranch_execz .LBB0_728
	s_nop 0
	v_lshl_add_u32 v0, s22, 8, v146
	v_ashrrev_i32_e32 v1, 31, v0
	v_lshl_add_u64 v[0:1], v[0:1], 4, s[88:89]
	global_load_dwordx4 v[0:3], v[0:1], off
